# FFN-up0 head: sample-row fix-up rows moved from workgroups 0..127 to 128..255 (off the five-unit workgroups)
# baseline (speedup 1.0000x reference)
; template <bool FINAL>
; __device__ __forceinline__ void sample_fixup(const Params& p, int S, float* ss_s, const float* gf) {
;     int tid_ = threadIdx.x; asm volatile("" : "+v"(tid_)); const int tid = tid_, lane = tid & 63, wave = tid >> 6;
;     const int gw = blockIdx.x * 8 + wave, NGW = gridDim.x * 8;
;     const float* part = (const float*)(p.ws + WS_PART); bf16* XB = (bf16*)(p.ws + WS_XB) + (size_t)MP * D; float* xo = p.out + (size_t)MP * D;
;     for (int r = gw; r < MS; r += NGW) {
;         f32x4 v[4];
;         unsigned long long* o8 = (unsigned long long*)(XB + (size_t)r * D) + lane;
; template <int layer>
; __device__ __forceinline__ void run_layer(const Params& p, LAS unsigned char* lds, const XcdBarrier& xbar, const int lo, const int hi) {
;     ...
;         if (IN(pb + 4)) {
;             {
;                 sample_fixup<false>(p, S_OUT, ss_mid + MP, nullptr);
.LBB0_464:
	s_add_u32 s40, s72, 0x1000000
	s_addc_u32 s41, s73, 0
	s_cmp_lt_i32 s74, 6
	s_cselect_b64 s[46:47], -1, 0
	s_cmp_gt_i32 s74, 5
	s_cselect_b64 s[0:1], -1, 0
	s_cmp_lt_i32 s75, 6
	s_cselect_b64 s[2:3], -1, 0
	s_or_b64 s[0:1], s[0:1], s[2:3]
	s_and_b64 vcc, exec, s[0:1]
	s_cbranch_vccnz .LBB0_521
	s_waitcnt vmcnt(0)
	v_mov_b32_e32 v1, v238
	s_movk_i32 s0, 0x400
	v_ashrrev_i32_e32 v0, 6, v1
	s_sub_i32 s2, s33, 0x80
	v_lshl_add_u32 v0, s2, 3, v0
	v_cmp_gt_u32_e32 vcc, s0, v0
	s_and_saveexec_b64 s[4:5], vcc
	s_cbranch_execz .LBB0_470
	v_and_b32_e32 v6, 63, v1
	v_mbcnt_lo_u32_b32 v1, -1, 0
	v_mbcnt_hi_u32_b32 v1, -1, v1
	v_and_b32_e32 v2, 64, v1
	v_add_u32_e32 v2, 64, v2
	v_xor_b32_e32 v3, 1, v1
	v_cmp_lt_i32_e32 vcc, v3, v2
	s_lshl_b32 s50, s10, 3
	s_ashr_i32 s51, s50, 31
	v_cndmask_b32_e32 v3, v1, v3, vcc
	v_lshlrev_b32_e32 v8, 2, v3
	v_xor_b32_e32 v3, 2, v1
	v_cmp_lt_i32_e32 vcc, v3, v2
	v_cmp_eq_u32_e64 s[0:1], 0, v6
	s_lshl_b64 s[52:53], s[50:51], 2
	v_cndmask_b32_e32 v3, v1, v3, vcc
	v_lshlrev_b32_e32 v9, 2, v3
	v_xor_b32_e32 v3, 4, v1
	v_cmp_lt_i32_e32 vcc, v3, v2
	s_lshl_b64 s[54:55], s[50:51], 11
	s_mov_b64 s[56:57], 0
	v_cndmask_b32_e32 v3, v1, v3, vcc
	v_lshlrev_b32_e32 v10, 2, v3
	v_xor_b32_e32 v3, 8, v1
	v_cmp_lt_i32_e32 vcc, v3, v2
	s_mov_b32 s6, 0xdb00000
	s_mov_b32 s7, 0xdd00000
	v_cndmask_b32_e32 v3, v1, v3, vcc
	v_lshlrev_b32_e32 v11, 2, v3
	v_xor_b32_e32 v3, 16, v1
	v_cmp_lt_i32_e32 vcc, v3, v2
	s_mov_b32 s8, 0xdf00000
	s_mov_b32 s9, 0xe100000
	v_cndmask_b32_e32 v3, v1, v3, vcc
	v_lshlrev_b32_e32 v12, 2, v3
	v_xor_b32_e32 v3, 32, v1
	v_cmp_lt_i32_e32 vcc, v3, v2
	s_movk_i32 s12, 0x3ff
	s_nop 0
	v_cndmask_b32_e32 v1, v1, v3, vcc
	v_lshlrev_b32_e32 v13, 2, v1
	v_ashrrev_i32_e32 v1, 31, v0
	v_mov_b64_e32 v[2:3], 0x21000
	v_lshlrev_b64 v[4:5], 11, v[0:1]
	v_lshl_add_u64 v[2:3], v[0:1], 2, v[2:3]
	v_lshl_or_b32 v4, v6, 3, v4
	s_branch .LBB0_468
